# adds: attention sink loads ahead of stores, tail GEMM items grouped per XCD, barrier poll cap raised
# speedup vs baseline: 1.0071x; 1.0071x over previous
.Lxb0_loop:
	global_load_dword v4, v3, s[4:5] sc1
	s_waitcnt vmcnt(0)
	v_readfirstlane_b32 s21, v4
	s_cmp_ge_u32 s21, s17
	s_cbranch_scc1 .Lxb0_done
	s_sleep 1
	s_add_i32 s16, s16, 1
	s_cmp_lt_u32 s16, 0x100000
	s_cbranch_scc1 .Lxb0_loop

.LBB0_768:
	v_readlane_b32 s0, v252, 62
	v_cndmask_b32_e64 v0, 0, 1, s[10:11]
	v_readlane_b32 s1, v252, 63
	v_cmp_ne_u32_e64 s[40:41], 1, v0
	s_andn2_b64 vcc, exec, s[10:11]
	v_cndmask_b32_e64 v0, 0, 1, s[0:1]
	v_cmp_ne_u32_e64 s[38:39], 1, v0
	s_cbranch_vccnz .LBB0_774
	v_mov_b32_e32 v6, v213
	s_and_b64 vcc, exec, s[38:39]
	v_readfirstlane_b32 s0, v6
	s_cbranch_vccnz .LBB0_774
	v_readlane_b32 s2, v253, 59
	s_ashr_i32 s1, s0, 6
	v_and_b32_e32 v2, 48, v6
	v_readlane_b32 s3, v253, 60
	s_andn2_b32 s0, s0, 63
	s_lshl_b32 s10, s1, 7
	v_lshl_add_u64 v[4:5], s[2:3], 0, v[2:3]
	s_lshl_b32 s2, s1, 12
	s_add_i32 s16, s2, 0
	s_cmp_lt_i32 s1, 4
	v_lshl_add_u64 v[0:1], s[96:97], 0, v[2:3]
	s_cselect_b64 s[2:3], -1, 0
	s_lshl_b32 s4, s0, 4
	v_lshlrev_b32_e32 v2, 4, v6
	v_and_b32_e32 v18, 15, v6
	s_add_i32 s4, s4, 0
	v_and_b32_e32 v2, 0x3f0, v2
	v_lshrrev_b32_e32 v6, 2, v6
	v_add_u32_e32 v19, s4, v2
	v_and_b32_e32 v6, 12, v6
	s_ashr_i32 s11, s10, 31
	s_add_i32 s4, s0, 0x400
	s_add_i32 s8, s0, 0x420
	v_lshl_or_b32 v20, s1, 4, v6
	s_ashr_i32 s5, s4, 31
	s_ashr_i32 s9, s8, 31
	v_add_u32_e32 v21, s16, v2
	v_or_b32_e32 v22, 0x4000, v18
	s_ashr_i32 s1, s0, 31
	s_lshl_b64 s[10:11], s[10:11], 1
	s_cmpk_lg_u32 s88, 0x100
	s_cbranch_scc1 .Ltperm0_o
	s_lshr_b32 s18, s91, 3
	s_and_b32 s18, s18, 7
	s_and_b32 s16, s91, 7
	s_lshr_b32 s17, s91, 6
	s_lshl_b32 s17, s17, 3
	s_add_i32 s16, s16, s17
	s_lshl_b32 s16, s16, 3
	s_add_i32 s18, s18, s16
	s_lshl_b32 s17, s18, 3
	s_lshl_b32 s16, s18, 4
	s_branch .Ltperm0_d
.Ltperm0_o:
	v_readlane_b32 s16, v252, 29
	v_readlane_b32 s17, v251, 2
	s_mov_b32 s18, s91
.Ltperm0_d:
	s_branch .LBB0_772
.LBB0_771:
	s_add_i32 s18, s18, s88
	s_add_i32 s17, s17, s90
	s_add_i32 s16, s16, s86
	s_cmpk_lt_i32 s18, 0x80
	s_barrier
	s_cbranch_scc0 .LBB0_774

.LBB0_845:
	s_and_b64 vcc, exec, s[40:41]
	v_readlane_b32 s18, v255, 36
	s_cbranch_vccnz .LBB0_851
	v_mov_b32_e32 v9, v213
	s_and_b64 vcc, exec, s[38:39]
	v_readfirstlane_b32 s3, v9
	s_cbranch_vccnz .LBB0_851
	s_ashr_i32 s4, s3, 6
	s_lshl_b32 s0, s4, 7
	s_ashr_i32 s1, s0, 31
	v_readlane_b32 s8, v253, 15
	v_and_b32_e32 v0, 63, v9
	v_and_b32_e32 v2, 48, v9
	s_lshl_b64 s[0:1], s[0:1], 1
	v_readlane_b32 s9, v253, 16
	s_lshl_b32 s2, s4, 12
	v_lshl_add_u32 v7, v0, 4, 0
	v_lshl_add_u64 v[0:1], s[68:69], 0, v[2:3]
	v_lshl_add_u64 v[4:5], s[8:9], 0, v[2:3]
	s_cmp_lt_i32 s4, 4
	v_lshrrev_b32_e32 v2, 2, v9
	v_lshl_add_u64 v[0:1], v[0:1], 0, s[0:1]
	v_lshl_add_u64 v[4:5], v[4:5], 0, s[0:1]
	s_cselect_b64 s[0:1], -1, 0
	s_and_b32 s3, s3, 0xfffffc0
	v_and_b32_e32 v2, 12, v2
	v_and_b32_e32 v6, 15, v9
	v_lshl_add_u32 v8, s3, 4, v7
	v_lshl_or_b32 v9, s4, 4, v2
	s_cmpk_lg_u32 s88, 0x100
	s_cbranch_scc1 .Ltperm1_o
	s_lshr_b32 s5, s91, 3
	s_and_b32 s5, s5, 7
	s_and_b32 s3, s91, 7
	s_lshr_b32 s4, s91, 6
	s_lshl_b32 s4, s4, 3
	s_add_i32 s3, s3, s4
	s_lshl_b32 s3, s3, 3
	s_add_i32 s5, s5, s3
	s_lshl_b32 s4, s5, 3
	s_lshl_b32 s3, s5, 4
	s_branch .Ltperm1_d
.Ltperm1_o:
	v_readlane_b32 s3, v252, 29
	v_readlane_b32 s4, v251, 2
	s_mov_b32 s5, s91
.Ltperm1_d:
	s_branch .LBB0_849
.LBB0_848:
	s_add_i32 s5, s5, s88
	s_add_i32 s4, s4, s90
	s_add_i32 s3, s3, s86
	s_cmpk_lt_i32 s5, 0x80
	s_barrier
	s_cbranch_scc0 .LBB0_851

.LBB0_1103:
	s_and_b64 vcc, exec, s[40:41]
	s_cbranch_vccnz .LBB0_1109
	v_readlane_b32 s2, v253, 6
	v_mov_b32_e32 v9, v213
	v_readlane_b32 s3, v253, 7
	s_andn2_b64 vcc, exec, s[2:3]
	v_readfirstlane_b32 s5, v9
	s_cbranch_vccnz .LBB0_1109
	v_readlane_b32 s2, v253, 30
	v_and_b32_e32 v0, 63, v9
	s_ashr_i32 s8, s5, 6
	v_and_b32_e32 v2, 48, v9
	v_readlane_b32 s3, v253, 31
	v_lshl_add_u32 v7, v0, 4, 0
	v_readlane_b32 s10, v253, 32
	v_lshl_add_u64 v[0:1], s[2:3], 0, v[2:3]
	s_lshl_b32 s2, s8, 7
	s_ashr_i32 s3, s2, 31
	s_lshl_b64 s[2:3], s[2:3], 1
	v_readlane_b32 s11, v253, 33
	s_lshl_b32 s4, s8, 12
	s_cmp_lt_i32 s8, 4
	v_lshl_add_u64 v[4:5], s[10:11], 0, v[2:3]
	v_lshrrev_b32_e32 v2, 2, v9
	v_and_b32_e32 v6, 15, v9
	v_lshl_add_u64 v[0:1], v[0:1], 0, s[2:3]
	v_lshl_add_u64 v[4:5], v[4:5], 0, s[2:3]
	s_cselect_b64 s[2:3], -1, 0
	s_and_b32 s5, s5, 0xfffffc0
	v_and_b32_e32 v2, 12, v2
	v_lshl_add_u32 v8, s5, 4, v7
	v_lshl_or_b32 v9, s8, 4, v2
	v_or_b32_e32 v10, 0x4000, v6
	s_cmpk_lg_u32 s88, 0x100
	s_cbranch_scc1 .Ltperm2_o
	s_lshr_b32 s9, s91, 3
	s_and_b32 s9, s9, 7
	s_and_b32 s5, s91, 7
	s_lshr_b32 s8, s91, 6
	s_lshl_b32 s8, s8, 3
	s_add_i32 s5, s5, s8
	s_lshl_b32 s5, s5, 3
	s_add_i32 s9, s9, s5
	s_lshl_b32 s8, s9, 3
	s_lshl_b32 s5, s9, 4
	s_branch .Ltperm2_d
.Ltperm2_o:
	v_readlane_b32 s5, v252, 29
	v_readlane_b32 s8, v251, 2
	s_mov_b32 s9, s91
.Ltperm2_d:
	s_branch .LBB0_1107
.LBB0_1106:
	s_add_i32 s9, s9, s88
	s_add_i32 s8, s8, s90
	s_add_i32 s5, s5, s86
	s_cmpk_lt_i32 s9, 0x200
	s_barrier
	s_cbranch_scc0 .LBB0_1109

.LBB0_1180:
	s_and_b64 vcc, exec, s[40:41]
	s_cbranch_vccnz .LBB0_1186
	v_mov_b32_e32 v6, v213
	s_and_b64 vcc, exec, s[38:39]
	v_readfirstlane_b32 s5, v6
	s_cbranch_vccnz .LBB0_1186
	s_ashr_i32 s8, s5, 6
	s_lshl_b32 s2, s8, 9
	s_ashr_i32 s3, s2, 31
	v_readlane_b32 s10, v253, 44
	v_and_b32_e32 v0, 63, v6
	v_and_b32_e32 v2, 48, v6
	s_lshl_b64 s[2:3], s[2:3], 1
	v_readlane_b32 s11, v253, 45
	s_lshl_b32 s4, s8, 12
	v_lshl_add_u32 v17, v0, 4, 0
	v_lshl_add_u64 v[0:1], s[94:95], 0, v[2:3]
	v_lshl_add_u64 v[4:5], s[10:11], 0, v[2:3]
	s_cmp_lt_i32 s8, 4
	v_lshrrev_b32_e32 v2, 2, v6
	v_and_b32_e32 v16, 15, v6
	v_lshl_add_u64 v[0:1], v[0:1], 0, s[2:3]
	v_lshl_add_u64 v[4:5], v[4:5], 0, s[2:3]
	s_cselect_b64 s[2:3], -1, 0
	s_and_b32 s5, s5, 0xfffffc0
	v_and_b32_e32 v2, 12, v2
	v_lshl_add_u32 v18, s5, 4, v17
	v_lshl_or_b32 v19, s8, 4, v2
	v_or_b32_e32 v20, 0x4000, v16
	s_cmpk_lg_u32 s88, 0x100
	s_cbranch_scc1 .Ltperm3_o
	s_lshr_b32 s9, s91, 3
	s_and_b32 s9, s9, 7
	s_and_b32 s5, s91, 7
	s_lshr_b32 s8, s91, 6
	s_lshl_b32 s8, s8, 3
	s_add_i32 s5, s5, s8
	s_lshl_b32 s5, s5, 3
	s_add_i32 s9, s9, s5
	s_lshl_b32 s8, s9, 3
	s_lshl_b32 s5, s9, 4
	s_branch .Ltperm3_d

.Ltperm3_d:
	s_mov_b32 s16, 0x20000
	s_mov_b32 s17, 0x40000
	s_branch .LBB0_1184
